# MLA tile body: shallower LDS prefetch (4 K-fragment buffers instead of 8, 3 V buffers instead of 5); rest as v20
# baseline (speedup 1.0000x reference)
.LBB0_1558:
	s_add_i32 s50, s46, -1
	v_min_u32_e32 v0, s50, v205
	v_mad_u64_u32 v[2:3], s[50:51], v0, s30, v[208:209]
	v_lshlrev_b32_e32 v0, 6, v0
	v_lshl_add_u64 v[4:5], v[0:1], 1, v[206:207]
	v_add_u32_e32 v0, 0xa800, v222
	s_add_i32 s47, s46, -4
	s_waitcnt vmcnt(7)
	ds_write_b128 v216, v[164:167] offset:43008
	s_waitcnt vmcnt(8)
	ds_write_b128 v217, v[160:163] offset:43008
	s_waitcnt vmcnt(7)
	ds_write_b128 v218, v[168:171] offset:43008
	s_waitcnt vmcnt(3)
	ds_write2_b64 v0, v[180:181], v[182:183] offset1:1
	v_add_u32_e32 v0, 0xca00, v222
	s_waitcnt vmcnt(1)
	ds_write2_b64 v0, v[188:189], v[190:191] offset1:1
	v_add_co_u32_e32 v6, vcc, 0x2000, v2
	s_nop 1
	v_addc_co_u32_e32 v7, vcc, 0, v3, vcc
	v_add_co_u32_e32 v8, vcc, 0x4000, v2
	s_nop 1
	v_addc_co_u32_e32 v9, vcc, 0, v3, vcc
	global_load_dwordx4 v[160:163], v[6:7], off
	global_load_dwordx4 v[168:171], v[8:9], off
	global_load_dwordx4 v[164:167], v[2:3], off
	global_load_dwordx4 v[180:183], v[4:5], off
	v_add_co_u32_e32 v2, vcc, 0x310000, v4
	s_nop 1
	v_addc_co_u32_e32 v3, vcc, 0, v5, vcc
	global_load_dwordx4 v[188:191], v[2:3], off
	s_cmp_ge_i32 s47, s43
	s_cbranch_scc1 .LBB0_1562
	ds_read_b128 v[4:7], v225
	ds_read_b128 v[8:11], v225 offset:12800
	ds_read_b128 v[12:15], v225 offset:32
	s_waitcnt lgkmcnt(2)
	v_mfma_f32_32x32x16_bf16 v[96:111], v[4:7], v[156:159], 0
	ds_read_b128 v[228:231], v225 offset:12832
	s_waitcnt lgkmcnt(2)
	v_mfma_f32_32x32x16_bf16 v[80:95], v[8:11], v[156:159], 0
	ds_read_b128 v[4:7], v225 offset:64
	s_waitcnt lgkmcnt(2)
	v_mfma_f32_32x32x16_bf16 v[96:111], v[12:15], v[152:155], v[96:111]
	ds_read_b128 v[8:11], v225 offset:12864
	s_waitcnt lgkmcnt(2)
	v_mfma_f32_32x32x16_bf16 v[80:95], v[228:231], v[152:155], v[80:95]
	ds_read_b128 v[12:15], v225 offset:96
	s_waitcnt lgkmcnt(2)
	v_mfma_f32_32x32x16_bf16 v[96:111], v[4:7], v[148:151], v[96:111]
	ds_read_b128 v[228:231], v225 offset:12896
	s_waitcnt lgkmcnt(2)
	v_mfma_f32_32x32x16_bf16 v[80:95], v[8:11], v[148:151], v[80:95]
	ds_read_b128 v[4:7], v225 offset:128
	s_waitcnt lgkmcnt(2)
	v_mfma_f32_32x32x16_bf16 v[96:111], v[12:15], v[144:147], v[96:111]
	ds_read_b128 v[8:11], v225 offset:12928
	s_waitcnt lgkmcnt(2)
	v_mfma_f32_32x32x16_bf16 v[80:95], v[228:231], v[144:147], v[80:95]
	ds_read_b128 v[12:15], v225 offset:160
	s_waitcnt lgkmcnt(2)
	v_mfma_f32_32x32x16_bf16 v[96:111], v[4:7], v[140:143], v[96:111]
	ds_read_b128 v[228:231], v225 offset:12960
	s_waitcnt lgkmcnt(2)
	v_mfma_f32_32x32x16_bf16 v[80:95], v[8:11], v[140:143], v[80:95]
	ds_read_b128 v[4:7], v225 offset:192
	s_waitcnt lgkmcnt(2)
	v_mfma_f32_32x32x16_bf16 v[96:111], v[12:15], v[136:139], v[96:111]
	ds_read_b128 v[8:11], v225 offset:12992
	s_waitcnt lgkmcnt(2)
	v_mfma_f32_32x32x16_bf16 v[80:95], v[228:231], v[136:139], v[80:95]
	ds_read_b128 v[12:15], v225 offset:224
	s_waitcnt lgkmcnt(2)
	v_mfma_f32_32x32x16_bf16 v[96:111], v[4:7], v[132:135], v[96:111]
	ds_read_b128 v[228:231], v225 offset:13024
	s_waitcnt lgkmcnt(2)
	v_mfma_f32_32x32x16_bf16 v[80:95], v[8:11], v[132:135], v[80:95]
	ds_read_b128 v[4:7], v225 offset:256
	s_waitcnt lgkmcnt(2)
	v_mfma_f32_32x32x16_bf16 v[96:111], v[12:15], v[128:131], v[96:111]
	ds_read_b128 v[8:11], v225 offset:13056
	s_waitcnt lgkmcnt(2)
	v_mfma_f32_32x32x16_bf16 v[80:95], v[228:231], v[128:131], v[80:95]
	ds_read_b128 v[12:15], v225 offset:288
	s_waitcnt lgkmcnt(2)
	v_mfma_f32_32x32x16_bf16 v[96:111], v[4:7], v[124:127], v[96:111]
	ds_read_b128 v[228:231], v225 offset:13088
	s_waitcnt lgkmcnt(2)
	v_mfma_f32_32x32x16_bf16 v[80:95], v[8:11], v[124:127], v[80:95]
	ds_read_b128 v[4:7], v225 offset:320
	s_waitcnt lgkmcnt(2)
	v_mfma_f32_32x32x16_bf16 v[96:111], v[12:15], v[120:123], v[96:111]
	ds_read_b128 v[8:11], v225 offset:13120
	s_waitcnt lgkmcnt(2)
	v_mfma_f32_32x32x16_bf16 v[80:95], v[228:231], v[120:123], v[80:95]
	ds_read_b128 v[12:15], v225 offset:352
	s_waitcnt lgkmcnt(2)
	v_mfma_f32_32x32x16_bf16 v[96:111], v[4:7], v[116:119], v[96:111]
	ds_read_b128 v[228:231], v225 offset:13152
	s_waitcnt lgkmcnt(2)
	v_mfma_f32_32x32x16_bf16 v[80:95], v[8:11], v[116:119], v[80:95]
	s_waitcnt lgkmcnt(1)
	v_mfma_f32_32x32x16_bf16 v[96:111], v[12:15], v[112:115], v[96:111]
	s_waitcnt lgkmcnt(0)
	v_mfma_f32_32x32x16_bf16 v[80:95], v[228:231], v[112:115], v[80:95]
	v_and_b32_e32 v248, 64, v210
	v_xor_b32_e32 v249, 32, v210
	v_add_u32_e32 v248, 64, v248
	v_cmp_lt_i32_e32 vcc, v249, v248
	ds_read_b64 v[232:233], v223 offset:25600
	ds_read_b64 v[234:235], v223 offset:25616
	ds_read_b64 v[236:237], v223 offset:29952
	ds_read_b64 v[238:239], v223 offset:29968
	ds_read_b64 v[240:241], v223 offset:34304
	ds_read_b64 v[242:243], v223 offset:34320
	v_cndmask_b32_e32 v249, v210, v249, vcc
	v_lshlrev_b32_e32 v249, 2, v249
	s_nop 1
	v_max_f32_e32 v0, v96, v80
	v_max3_f32 v0, v0, v97, v81
	v_max3_f32 v0, v0, v98, v82
	v_max3_f32 v0, v0, v99, v83
	v_max3_f32 v0, v0, v100, v84
	v_max3_f32 v0, v0, v101, v85
	v_max3_f32 v0, v0, v102, v86
	v_max3_f32 v0, v0, v103, v87
	v_max3_f32 v0, v0, v104, v88
	v_max3_f32 v0, v0, v105, v89
	v_max3_f32 v0, v0, v106, v90
	v_max3_f32 v0, v0, v107, v91
	v_max3_f32 v0, v0, v108, v92
	v_max3_f32 v0, v0, v109, v93
	v_max3_f32 v0, v0, v110, v94
	v_max3_f32 v0, v0, v111, v95
	ds_bpermute_b32 v248, v249, v0
	s_waitcnt lgkmcnt(0)
	v_max_f32_e32 v0, v0, v248
	v_max_f32_e32 v248, v226, v226
	v_max_f32_e32 v0, v0, v0
	v_sub_f32_e32 v249, v0, v248
	v_cmp_lt_f32_e32 vcc, 0x41000000, v249
	s_cbranch_vccz .Lmla_keep_a
	v_max_f32_e32 v2, v248, v0
	v_sub_f32_e32 v0, v226, v2
	v_exp_f32_e32 v0, v0
	s_nop 0
	v_pk_mul_f32 v[78:79], v[78:79], v[0:1] op_sel_hi:[1,0]
	v_pk_mul_f32 v[76:77], v[76:77], v[0:1] op_sel_hi:[1,0]
	v_pk_mul_f32 v[74:75], v[74:75], v[0:1] op_sel_hi:[1,0]
	v_pk_mul_f32 v[72:73], v[72:73], v[0:1] op_sel_hi:[1,0]
	v_pk_mul_f32 v[70:71], v[70:71], v[0:1] op_sel_hi:[1,0]
	v_pk_mul_f32 v[68:69], v[68:69], v[0:1] op_sel_hi:[1,0]
	v_pk_mul_f32 v[66:67], v[66:67], v[0:1] op_sel_hi:[1,0]
	v_pk_mul_f32 v[64:65], v[64:65], v[0:1] op_sel_hi:[1,0]
	v_pk_mul_f32 v[62:63], v[62:63], v[0:1] op_sel_hi:[1,0]
	v_pk_mul_f32 v[60:61], v[60:61], v[0:1] op_sel_hi:[1,0]
	v_pk_mul_f32 v[58:59], v[58:59], v[0:1] op_sel_hi:[1,0]
	v_pk_mul_f32 v[56:57], v[56:57], v[0:1] op_sel_hi:[1,0]
	v_pk_mul_f32 v[54:55], v[54:55], v[0:1] op_sel_hi:[1,0]
	v_pk_mul_f32 v[52:53], v[52:53], v[0:1] op_sel_hi:[1,0]
	v_pk_mul_f32 v[50:51], v[50:51], v[0:1] op_sel_hi:[1,0]
	v_pk_mul_f32 v[48:49], v[48:49], v[0:1] op_sel_hi:[1,0]
	v_pk_mul_f32 v[46:47], v[46:47], v[0:1] op_sel_hi:[1,0]
	v_pk_mul_f32 v[44:45], v[44:45], v[0:1] op_sel_hi:[1,0]
	v_pk_mul_f32 v[42:43], v[42:43], v[0:1] op_sel_hi:[1,0]
	v_pk_mul_f32 v[40:41], v[40:41], v[0:1] op_sel_hi:[1,0]
	v_pk_mul_f32 v[38:39], v[38:39], v[0:1] op_sel_hi:[1,0]
	v_pk_mul_f32 v[36:37], v[36:37], v[0:1] op_sel_hi:[1,0]
	v_pk_mul_f32 v[34:35], v[34:35], v[0:1] op_sel_hi:[1,0]
	v_pk_mul_f32 v[32:33], v[32:33], v[0:1] op_sel_hi:[1,0]
	v_pk_mul_f32 v[30:31], v[30:31], v[0:1] op_sel_hi:[1,0]
	v_pk_mul_f32 v[28:29], v[28:29], v[0:1] op_sel_hi:[1,0]
	v_pk_mul_f32 v[26:27], v[26:27], v[0:1] op_sel_hi:[1,0]
	v_pk_mul_f32 v[24:25], v[24:25], v[0:1] op_sel_hi:[1,0]
	v_pk_mul_f32 v[22:23], v[22:23], v[0:1] op_sel_hi:[1,0]
	v_pk_mul_f32 v[20:21], v[20:21], v[0:1] op_sel_hi:[1,0]
	v_pk_mul_f32 v[18:19], v[18:19], v[0:1] op_sel_hi:[1,0]
	v_pk_mul_f32 v[16:17], v[16:17], v[0:1] op_sel_hi:[1,0]
	s_branch .Lmla_join_a
	.Lmla_keep_a:
	v_mov_b32_e32 v2, v248
	v_mov_b32_e32 v0, 1.0
	.Lmla_join_a:
	v_sub_f32_e32 v248, v96, v2
	v_exp_f32_e32 v96, v248
	v_sub_f32_e32 v249, v97, v2
	v_exp_f32_e32 v97, v249
	v_sub_f32_e32 v248, v98, v2
	v_exp_f32_e32 v98, v248
	v_sub_f32_e32 v249, v99, v2
	v_exp_f32_e32 v99, v249
	v_sub_f32_e32 v248, v100, v2
	v_exp_f32_e32 v100, v248
	v_sub_f32_e32 v249, v101, v2
	v_exp_f32_e32 v101, v249
	v_sub_f32_e32 v248, v102, v2
	v_exp_f32_e32 v102, v248
	v_sub_f32_e32 v249, v103, v2
	v_exp_f32_e32 v103, v249
	s_nop 0
	v_cvt_pk_bf16_f32 v8, v96, v97
	v_cvt_pk_bf16_f32 v9, v98, v99
	v_cvt_pk_bf16_f32 v10, v100, v101
	v_cvt_pk_bf16_f32 v11, v102, v103
	v_sub_f32_e32 v248, v104, v2
	v_exp_f32_e32 v104, v248
	v_mfma_f32_32x32x16_bf16 v[64:79], v[232:235], v[8:11], v[64:79]
	ds_read_b64 v[232:233], v223 offset:38656
	ds_read_b64 v[234:235], v223 offset:38672
	v_sub_f32_e32 v249, v105, v2
	v_exp_f32_e32 v105, v249
	v_mfma_f32_32x32x16_bf16 v[48:63], v[236:239], v[8:11], v[48:63]
	ds_read_b64 v[236:237], v223 offset:25632
	ds_read_b64 v[238:239], v223 offset:25648
	v_sub_f32_e32 v248, v106, v2
	v_exp_f32_e32 v106, v248
	v_sub_f32_e32 v249, v107, v2
	v_exp_f32_e32 v107, v249
	v_mfma_f32_32x32x16_bf16 v[32:47], v[240:243], v[8:11], v[32:47]
	ds_read_b64 v[240:241], v223 offset:29984
	ds_read_b64 v[242:243], v223 offset:30000
	v_sub_f32_e32 v248, v108, v2
	v_exp_f32_e32 v108, v248
	v_sub_f32_e32 v249, v109, v2
	v_exp_f32_e32 v109, v249
	s_waitcnt lgkmcnt(4)
	v_mfma_f32_32x32x16_bf16 v[16:31], v[232:235], v[8:11], v[16:31]
	ds_read_b64 v[232:233], v223 offset:34336
	ds_read_b64 v[234:235], v223 offset:34352
	v_sub_f32_e32 v248, v110, v2
	v_exp_f32_e32 v110, v248
	v_sub_f32_e32 v249, v111, v2
	v_exp_f32_e32 v111, v249
	s_nop 0
	v_cvt_pk_bf16_f32 v4, v104, v105
	v_cvt_pk_bf16_f32 v5, v106, v107
	v_cvt_pk_bf16_f32 v6, v108, v109
	v_cvt_pk_bf16_f32 v7, v110, v111
	s_nop 1
	s_waitcnt lgkmcnt(4)
	v_mfma_f32_32x32x16_bf16 v[64:79], v[236:239], v[4:7], v[64:79]
	ds_read_b64 v[236:237], v223 offset:38688
	ds_read_b64 v[238:239], v223 offset:38704
	v_sub_f32_e32 v248, v80, v2
	v_exp_f32_e32 v80, v248
	v_sub_f32_e32 v249, v81, v2
	v_exp_f32_e32 v81, v249
	s_waitcnt lgkmcnt(4)
	v_mfma_f32_32x32x16_bf16 v[48:63], v[240:243], v[4:7], v[48:63]
	ds_read_b64 v[240:241], v223 offset:25664
	ds_read_b64 v[242:243], v223 offset:25680
	v_sub_f32_e32 v248, v82, v2
	v_exp_f32_e32 v82, v248
	v_sub_f32_e32 v249, v83, v2
	v_exp_f32_e32 v83, v249
	s_waitcnt lgkmcnt(4)
	v_mfma_f32_32x32x16_bf16 v[32:47], v[232:235], v[4:7], v[32:47]
	ds_read_b64 v[232:233], v223 offset:30016
	ds_read_b64 v[234:235], v223 offset:30032
	v_sub_f32_e32 v248, v84, v2
	v_exp_f32_e32 v84, v248
	v_sub_f32_e32 v249, v85, v2
	v_exp_f32_e32 v85, v249
	s_waitcnt lgkmcnt(4)
	v_mfma_f32_32x32x16_bf16 v[16:31], v[236:239], v[4:7], v[16:31]
	ds_read_b64 v[236:237], v223 offset:34368
	ds_read_b64 v[238:239], v223 offset:34384
	v_sub_f32_e32 v248, v86, v2
	v_exp_f32_e32 v86, v248
	v_sub_f32_e32 v249, v87, v2
	v_exp_f32_e32 v87, v249
	s_nop 0
	v_cvt_pk_bf16_f32 v12, v80, v81
	v_cvt_pk_bf16_f32 v13, v82, v83
	v_cvt_pk_bf16_f32 v14, v84, v85
	v_cvt_pk_bf16_f32 v15, v86, v87
	s_nop 1
	s_waitcnt lgkmcnt(4)
	v_mfma_f32_32x32x16_bf16 v[64:79], v[240:243], v[12:15], v[64:79]
	ds_read_b64 v[240:241], v223 offset:38720
	ds_read_b64 v[242:243], v223 offset:38736
	v_sub_f32_e32 v248, v88, v2
	v_exp_f32_e32 v88, v248
	v_sub_f32_e32 v249, v89, v2
	v_exp_f32_e32 v89, v249
	s_waitcnt lgkmcnt(4)
	v_mfma_f32_32x32x16_bf16 v[48:63], v[232:235], v[12:15], v[48:63]
	ds_read_b64 v[232:233], v223 offset:25696
	ds_read_b64 v[234:235], v223 offset:25712
	v_sub_f32_e32 v248, v90, v2
	v_exp_f32_e32 v90, v248
	v_sub_f32_e32 v249, v91, v2
	v_exp_f32_e32 v91, v249
	s_waitcnt lgkmcnt(4)
	v_mfma_f32_32x32x16_bf16 v[32:47], v[236:239], v[12:15], v[32:47]
	ds_read_b64 v[236:237], v223 offset:30048
	ds_read_b64 v[238:239], v223 offset:30064
	v_sub_f32_e32 v248, v92, v2
	v_exp_f32_e32 v92, v248
	v_sub_f32_e32 v249, v93, v2
	v_exp_f32_e32 v93, v249
	s_waitcnt lgkmcnt(4)
	v_mfma_f32_32x32x16_bf16 v[16:31], v[240:243], v[12:15], v[16:31]
	ds_read_b64 v[240:241], v223 offset:34400
	ds_read_b64 v[242:243], v223 offset:34416
	v_sub_f32_e32 v248, v94, v2
	v_exp_f32_e32 v94, v248
	v_sub_f32_e32 v249, v95, v2
	v_exp_f32_e32 v95, v249
	s_nop 0
	v_cvt_pk_bf16_f32 v8, v88, v89
	v_cvt_pk_bf16_f32 v9, v90, v91
	v_cvt_pk_bf16_f32 v10, v92, v93
	v_cvt_pk_bf16_f32 v11, v94, v95
	s_nop 1
	s_waitcnt lgkmcnt(4)
	v_mfma_f32_32x32x16_bf16 v[64:79], v[232:235], v[8:11], v[64:79]
	ds_read_b64 v[232:233], v223 offset:38752
	ds_read_b64 v[234:235], v223 offset:38768
	v_add_f32_e32 v3, v80, v96
	v_add_f32_e32 v248, v81, v97
	v_add_f32_e32 v3, v248, v3
	v_add_f32_e32 v249, v82, v98
	v_add_f32_e32 v3, v249, v3
	v_add_f32_e32 v248, v83, v99
	v_add_f32_e32 v3, v248, v3
	v_add_f32_e32 v249, v84, v100
	s_waitcnt lgkmcnt(4)
	v_mfma_f32_32x32x16_bf16 v[48:63], v[236:239], v[8:11], v[48:63]
	v_add_f32_e32 v3, v249, v3
	v_add_f32_e32 v248, v85, v101
	v_add_f32_e32 v3, v248, v3
	v_add_f32_e32 v249, v86, v102
	v_add_f32_e32 v3, v249, v3
	v_add_f32_e32 v248, v87, v103
	v_add_f32_e32 v3, v248, v3
	v_add_f32_e32 v249, v88, v104
	s_waitcnt lgkmcnt(2)
	v_mfma_f32_32x32x16_bf16 v[32:47], v[240:243], v[8:11], v[32:47]
	v_add_f32_e32 v3, v249, v3
	v_add_f32_e32 v248, v89, v105
	v_add_f32_e32 v3, v248, v3
	v_add_f32_e32 v249, v90, v106
	v_add_f32_e32 v3, v249, v3
	v_add_f32_e32 v248, v91, v107
	v_add_f32_e32 v3, v248, v3
	v_add_f32_e32 v249, v92, v108
	s_waitcnt lgkmcnt(0)
	v_mfma_f32_32x32x16_bf16 v[16:31], v[232:235], v[8:11], v[16:31]
	v_add_f32_e32 v3, v249, v3
	v_add_f32_e32 v248, v93, v109
	v_add_f32_e32 v3, v248, v3
	v_add_f32_e32 v249, v94, v110
	v_add_f32_e32 v3, v249, v3
	v_add_f32_e32 v248, v95, v111
	v_add_f32_e32 v3, v248, v3
	v_fmac_f32_e32 v3, v221, v0
	v_mov_b32_e32 v221, v3
	s_branch .LBB0_1563

.LBB0_1563:
	v_min_u32_e32 v0, s46, v205
	v_mad_u64_u32 v[4:5], s[50:51], v0, s30, v[208:209]
	v_lshlrev_b32_e32 v0, 6, v0
	s_waitcnt lgkmcnt(0)
	s_barrier
	ds_write_b128 v216, v[172:175]
	ds_write_b128 v217, v[184:187]
	ds_write_b128 v218, v[192:195]
	v_lshl_add_u64 v[6:7], v[0:1], 1, v[206:207]
	ds_write2_b64 v219, v[176:177], v[178:179] offset1:1
	s_waitcnt vmcnt(5)
	ds_write2_b64 v220, v[196:197], v[198:199] offset1:1
	v_add_co_u32_e32 v8, vcc, 0x2000, v4
	s_nop 1
	v_addc_co_u32_e32 v9, vcc, 0, v5, vcc
	v_add_co_u32_e32 v10, vcc, 0x4000, v4
	s_nop 1
	v_addc_co_u32_e32 v11, vcc, 0, v5, vcc
	global_load_dwordx4 v[184:187], v[8:9], off
	global_load_dwordx4 v[192:195], v[10:11], off
	global_load_dwordx4 v[172:175], v[4:5], off
	global_load_dwordx4 v[176:179], v[6:7], off
	v_add_co_u32_e32 v4, vcc, 0x310000, v6
	s_nop 1
	v_addc_co_u32_e32 v5, vcc, 0, v7, vcc
	global_load_dwordx4 v[196:199], v[4:5], off
	s_add_i32 s47, s47, 1
	s_cmp_ge_i32 s47, s43
	s_cbranch_scc1 .LBB0_1556
	ds_read_b128 v[4:7], v225 offset:43008
	ds_read_b128 v[8:11], v225 offset:55808
	ds_read_b128 v[12:15], v225 offset:43040
	s_waitcnt lgkmcnt(2)
	v_mfma_f32_32x32x16_bf16 v[96:111], v[4:7], v[156:159], 0
	ds_read_b128 v[228:231], v225 offset:55840
	s_waitcnt lgkmcnt(2)
	v_mfma_f32_32x32x16_bf16 v[80:95], v[8:11], v[156:159], 0
	ds_read_b128 v[4:7], v225 offset:43072
	s_waitcnt lgkmcnt(2)
	v_mfma_f32_32x32x16_bf16 v[96:111], v[12:15], v[152:155], v[96:111]
	ds_read_b128 v[8:11], v225 offset:55872
	s_waitcnt lgkmcnt(2)
	v_mfma_f32_32x32x16_bf16 v[80:95], v[228:231], v[152:155], v[80:95]
	ds_read_b128 v[12:15], v225 offset:43104
	s_waitcnt lgkmcnt(2)
	v_mfma_f32_32x32x16_bf16 v[96:111], v[4:7], v[148:151], v[96:111]
	ds_read_b128 v[228:231], v225 offset:55904
	s_waitcnt lgkmcnt(2)
	v_mfma_f32_32x32x16_bf16 v[80:95], v[8:11], v[148:151], v[80:95]
	ds_read_b128 v[4:7], v225 offset:43136
	s_waitcnt lgkmcnt(2)
	v_mfma_f32_32x32x16_bf16 v[96:111], v[12:15], v[144:147], v[96:111]
	ds_read_b128 v[8:11], v225 offset:55936
	s_waitcnt lgkmcnt(2)
	v_mfma_f32_32x32x16_bf16 v[80:95], v[228:231], v[144:147], v[80:95]
	ds_read_b128 v[12:15], v225 offset:43168
	s_waitcnt lgkmcnt(2)
	v_mfma_f32_32x32x16_bf16 v[96:111], v[4:7], v[140:143], v[96:111]
	ds_read_b128 v[228:231], v225 offset:55968
	s_waitcnt lgkmcnt(2)
	v_mfma_f32_32x32x16_bf16 v[80:95], v[8:11], v[140:143], v[80:95]
	ds_read_b128 v[4:7], v225 offset:43200
	s_waitcnt lgkmcnt(2)
	v_mfma_f32_32x32x16_bf16 v[96:111], v[12:15], v[136:139], v[96:111]
	ds_read_b128 v[8:11], v225 offset:56000
	s_waitcnt lgkmcnt(2)
	v_mfma_f32_32x32x16_bf16 v[80:95], v[228:231], v[136:139], v[80:95]
	ds_read_b128 v[12:15], v225 offset:43232
	s_waitcnt lgkmcnt(2)
	v_mfma_f32_32x32x16_bf16 v[96:111], v[4:7], v[132:135], v[96:111]
	ds_read_b128 v[228:231], v225 offset:56032
	s_waitcnt lgkmcnt(2)
	v_mfma_f32_32x32x16_bf16 v[80:95], v[8:11], v[132:135], v[80:95]
	ds_read_b128 v[4:7], v225 offset:43264
	s_waitcnt lgkmcnt(2)
	v_mfma_f32_32x32x16_bf16 v[96:111], v[12:15], v[128:131], v[96:111]
	ds_read_b128 v[8:11], v225 offset:56064
	s_waitcnt lgkmcnt(2)
	v_mfma_f32_32x32x16_bf16 v[80:95], v[228:231], v[128:131], v[80:95]
	ds_read_b128 v[12:15], v225 offset:43296
	s_waitcnt lgkmcnt(2)
	v_mfma_f32_32x32x16_bf16 v[96:111], v[4:7], v[124:127], v[96:111]
	ds_read_b128 v[228:231], v225 offset:56096
	s_waitcnt lgkmcnt(2)
	v_mfma_f32_32x32x16_bf16 v[80:95], v[8:11], v[124:127], v[80:95]
	ds_read_b128 v[4:7], v225 offset:43328
	s_waitcnt lgkmcnt(2)
	v_mfma_f32_32x32x16_bf16 v[96:111], v[12:15], v[120:123], v[96:111]
	ds_read_b128 v[8:11], v225 offset:56128
	s_waitcnt lgkmcnt(2)
	v_mfma_f32_32x32x16_bf16 v[80:95], v[228:231], v[120:123], v[80:95]
	ds_read_b128 v[12:15], v225 offset:43360
	s_waitcnt lgkmcnt(2)
	v_mfma_f32_32x32x16_bf16 v[96:111], v[4:7], v[116:119], v[96:111]
	ds_read_b128 v[228:231], v225 offset:56160
	s_waitcnt lgkmcnt(2)
	v_mfma_f32_32x32x16_bf16 v[80:95], v[8:11], v[116:119], v[80:95]
	s_waitcnt lgkmcnt(1)
	v_mfma_f32_32x32x16_bf16 v[96:111], v[12:15], v[112:115], v[96:111]
	s_waitcnt lgkmcnt(0)
	v_mfma_f32_32x32x16_bf16 v[80:95], v[228:231], v[112:115], v[80:95]
	v_and_b32_e32 v248, 64, v210
	v_xor_b32_e32 v249, 32, v210
	v_add_u32_e32 v248, 64, v248
	v_cmp_lt_i32_e32 vcc, v249, v248
	ds_read_b64 v[232:233], v224 offset:0
	ds_read_b64 v[234:235], v224 offset:16
	ds_read_b64 v[236:237], v224 offset:4352
	ds_read_b64 v[238:239], v224 offset:4368
	ds_read_b64 v[240:241], v224 offset:8704
	ds_read_b64 v[242:243], v224 offset:8720
	v_cndmask_b32_e32 v249, v210, v249, vcc
	v_lshlrev_b32_e32 v249, 2, v249
	s_nop 1
	v_max_f32_e32 v0, v96, v80
	v_max3_f32 v0, v0, v97, v81
	v_max3_f32 v0, v0, v98, v82
	v_max3_f32 v0, v0, v99, v83
	v_max3_f32 v0, v0, v100, v84
	v_max3_f32 v0, v0, v101, v85
	v_max3_f32 v0, v0, v102, v86
	v_max3_f32 v0, v0, v103, v87
	v_max3_f32 v0, v0, v104, v88
	v_max3_f32 v0, v0, v105, v89
	v_max3_f32 v0, v0, v106, v90
	v_max3_f32 v0, v0, v107, v91
	v_max3_f32 v0, v0, v108, v92
	v_max3_f32 v0, v0, v109, v93
	v_max3_f32 v0, v0, v110, v94
	v_max3_f32 v0, v0, v111, v95
	ds_bpermute_b32 v248, v249, v0
	s_waitcnt lgkmcnt(0)
	v_max_f32_e32 v0, v0, v248
	v_max_f32_e32 v248, v2, v2
	v_max_f32_e32 v0, v0, v0
	v_sub_f32_e32 v249, v0, v248
	v_cmp_lt_f32_e32 vcc, 0x41000000, v249
	s_cbranch_vccz .Lmla_keep_b
	v_max_f32_e32 v226, v248, v0
	v_sub_f32_e32 v0, v2, v226
	v_exp_f32_e32 v0, v0
	s_nop 0
	v_pk_mul_f32 v[78:79], v[78:79], v[0:1] op_sel_hi:[1,0]
	v_pk_mul_f32 v[76:77], v[76:77], v[0:1] op_sel_hi:[1,0]
	v_pk_mul_f32 v[74:75], v[74:75], v[0:1] op_sel_hi:[1,0]
	v_pk_mul_f32 v[72:73], v[72:73], v[0:1] op_sel_hi:[1,0]
	v_pk_mul_f32 v[70:71], v[70:71], v[0:1] op_sel_hi:[1,0]
	v_pk_mul_f32 v[68:69], v[68:69], v[0:1] op_sel_hi:[1,0]
	v_pk_mul_f32 v[66:67], v[66:67], v[0:1] op_sel_hi:[1,0]
	v_pk_mul_f32 v[64:65], v[64:65], v[0:1] op_sel_hi:[1,0]
	v_pk_mul_f32 v[62:63], v[62:63], v[0:1] op_sel_hi:[1,0]
	v_pk_mul_f32 v[60:61], v[60:61], v[0:1] op_sel_hi:[1,0]
	v_pk_mul_f32 v[58:59], v[58:59], v[0:1] op_sel_hi:[1,0]
	v_pk_mul_f32 v[56:57], v[56:57], v[0:1] op_sel_hi:[1,0]
	v_pk_mul_f32 v[54:55], v[54:55], v[0:1] op_sel_hi:[1,0]
	v_pk_mul_f32 v[52:53], v[52:53], v[0:1] op_sel_hi:[1,0]
	v_pk_mul_f32 v[50:51], v[50:51], v[0:1] op_sel_hi:[1,0]
	v_pk_mul_f32 v[48:49], v[48:49], v[0:1] op_sel_hi:[1,0]
	v_pk_mul_f32 v[46:47], v[46:47], v[0:1] op_sel_hi:[1,0]
	v_pk_mul_f32 v[44:45], v[44:45], v[0:1] op_sel_hi:[1,0]
	v_pk_mul_f32 v[42:43], v[42:43], v[0:1] op_sel_hi:[1,0]
	v_pk_mul_f32 v[40:41], v[40:41], v[0:1] op_sel_hi:[1,0]
	v_pk_mul_f32 v[38:39], v[38:39], v[0:1] op_sel_hi:[1,0]
	v_pk_mul_f32 v[36:37], v[36:37], v[0:1] op_sel_hi:[1,0]
	v_pk_mul_f32 v[34:35], v[34:35], v[0:1] op_sel_hi:[1,0]
	v_pk_mul_f32 v[32:33], v[32:33], v[0:1] op_sel_hi:[1,0]
	v_pk_mul_f32 v[30:31], v[30:31], v[0:1] op_sel_hi:[1,0]
	v_pk_mul_f32 v[28:29], v[28:29], v[0:1] op_sel_hi:[1,0]
	v_pk_mul_f32 v[26:27], v[26:27], v[0:1] op_sel_hi:[1,0]
	v_pk_mul_f32 v[24:25], v[24:25], v[0:1] op_sel_hi:[1,0]
	v_pk_mul_f32 v[22:23], v[22:23], v[0:1] op_sel_hi:[1,0]
	v_pk_mul_f32 v[20:21], v[20:21], v[0:1] op_sel_hi:[1,0]
	v_pk_mul_f32 v[18:19], v[18:19], v[0:1] op_sel_hi:[1,0]
	v_pk_mul_f32 v[16:17], v[16:17], v[0:1] op_sel_hi:[1,0]
	s_branch .Lmla_join_b
	.Lmla_keep_b:
	v_mov_b32_e32 v226, v248
	v_mov_b32_e32 v0, 1.0
	.Lmla_join_b:
	v_sub_f32_e32 v248, v96, v226
	v_exp_f32_e32 v96, v248
	v_sub_f32_e32 v249, v97, v226
	v_exp_f32_e32 v97, v249
	v_sub_f32_e32 v248, v98, v226
	v_exp_f32_e32 v98, v248
	v_sub_f32_e32 v249, v99, v226
	v_exp_f32_e32 v99, v249
	v_sub_f32_e32 v248, v100, v226
	v_exp_f32_e32 v100, v248
	v_sub_f32_e32 v249, v101, v226
	v_exp_f32_e32 v101, v249
	v_sub_f32_e32 v248, v102, v226
	v_exp_f32_e32 v102, v248
	v_sub_f32_e32 v249, v103, v226
	v_exp_f32_e32 v103, v249
	s_nop 0
	v_cvt_pk_bf16_f32 v8, v96, v97
	v_cvt_pk_bf16_f32 v9, v98, v99
	v_cvt_pk_bf16_f32 v10, v100, v101
	v_cvt_pk_bf16_f32 v11, v102, v103
	v_sub_f32_e32 v248, v104, v226
	v_exp_f32_e32 v104, v248
	v_mfma_f32_32x32x16_bf16 v[64:79], v[232:235], v[8:11], v[64:79]
	ds_read_b64 v[232:233], v224 offset:13056
	ds_read_b64 v[234:235], v224 offset:13072
	v_sub_f32_e32 v249, v105, v226
	v_exp_f32_e32 v105, v249
	v_mfma_f32_32x32x16_bf16 v[48:63], v[236:239], v[8:11], v[48:63]
	ds_read_b64 v[236:237], v224 offset:32
	ds_read_b64 v[238:239], v224 offset:48
	v_sub_f32_e32 v248, v106, v226
	v_exp_f32_e32 v106, v248
	v_sub_f32_e32 v249, v107, v226
	v_exp_f32_e32 v107, v249
	v_mfma_f32_32x32x16_bf16 v[32:47], v[240:243], v[8:11], v[32:47]
	ds_read_b64 v[240:241], v224 offset:4384
	ds_read_b64 v[242:243], v224 offset:4400
	v_sub_f32_e32 v248, v108, v226
	v_exp_f32_e32 v108, v248
	v_sub_f32_e32 v249, v109, v226
	v_exp_f32_e32 v109, v249
	s_waitcnt lgkmcnt(4)
	v_mfma_f32_32x32x16_bf16 v[16:31], v[232:235], v[8:11], v[16:31]
	ds_read_b64 v[232:233], v224 offset:8736
	ds_read_b64 v[234:235], v224 offset:8752
	v_sub_f32_e32 v248, v110, v226
	v_exp_f32_e32 v110, v248
	v_sub_f32_e32 v249, v111, v226
	v_exp_f32_e32 v111, v249
	s_nop 0
	v_cvt_pk_bf16_f32 v4, v104, v105
	v_cvt_pk_bf16_f32 v5, v106, v107
	v_cvt_pk_bf16_f32 v6, v108, v109
	v_cvt_pk_bf16_f32 v7, v110, v111
	s_nop 1
	s_waitcnt lgkmcnt(4)
	v_mfma_f32_32x32x16_bf16 v[64:79], v[236:239], v[4:7], v[64:79]
	ds_read_b64 v[236:237], v224 offset:13088
	ds_read_b64 v[238:239], v224 offset:13104
	v_sub_f32_e32 v248, v80, v226
	v_exp_f32_e32 v80, v248
	v_sub_f32_e32 v249, v81, v226
	v_exp_f32_e32 v81, v249
	s_waitcnt lgkmcnt(4)
	v_mfma_f32_32x32x16_bf16 v[48:63], v[240:243], v[4:7], v[48:63]
	ds_read_b64 v[240:241], v224 offset:64
	ds_read_b64 v[242:243], v224 offset:80
	v_sub_f32_e32 v248, v82, v226
	v_exp_f32_e32 v82, v248
	v_sub_f32_e32 v249, v83, v226
	v_exp_f32_e32 v83, v249
	s_waitcnt lgkmcnt(4)
	v_mfma_f32_32x32x16_bf16 v[32:47], v[232:235], v[4:7], v[32:47]
	ds_read_b64 v[232:233], v224 offset:4416
	ds_read_b64 v[234:235], v224 offset:4432
	v_sub_f32_e32 v248, v84, v226
	v_exp_f32_e32 v84, v248
	v_sub_f32_e32 v249, v85, v226
	v_exp_f32_e32 v85, v249
	s_waitcnt lgkmcnt(4)
	v_mfma_f32_32x32x16_bf16 v[16:31], v[236:239], v[4:7], v[16:31]
	ds_read_b64 v[236:237], v224 offset:8768
	ds_read_b64 v[238:239], v224 offset:8784
	v_sub_f32_e32 v248, v86, v226
	v_exp_f32_e32 v86, v248
	v_sub_f32_e32 v249, v87, v226
	v_exp_f32_e32 v87, v249
	s_nop 0
	v_cvt_pk_bf16_f32 v12, v80, v81
	v_cvt_pk_bf16_f32 v13, v82, v83
	v_cvt_pk_bf16_f32 v14, v84, v85
	v_cvt_pk_bf16_f32 v15, v86, v87
	s_nop 1
	s_waitcnt lgkmcnt(4)
	v_mfma_f32_32x32x16_bf16 v[64:79], v[240:243], v[12:15], v[64:79]
	ds_read_b64 v[240:241], v224 offset:13120
	ds_read_b64 v[242:243], v224 offset:13136
	v_sub_f32_e32 v248, v88, v226
	v_exp_f32_e32 v88, v248
	v_sub_f32_e32 v249, v89, v226
	v_exp_f32_e32 v89, v249
	s_waitcnt lgkmcnt(4)
	v_mfma_f32_32x32x16_bf16 v[48:63], v[232:235], v[12:15], v[48:63]
	ds_read_b64 v[232:233], v224 offset:96
	ds_read_b64 v[234:235], v224 offset:112
	v_sub_f32_e32 v248, v90, v226
	v_exp_f32_e32 v90, v248
	v_sub_f32_e32 v249, v91, v226
	v_exp_f32_e32 v91, v249
	s_waitcnt lgkmcnt(4)
	v_mfma_f32_32x32x16_bf16 v[32:47], v[236:239], v[12:15], v[32:47]
	ds_read_b64 v[236:237], v224 offset:4448
	ds_read_b64 v[238:239], v224 offset:4464
	v_sub_f32_e32 v248, v92, v226
	v_exp_f32_e32 v92, v248
	v_sub_f32_e32 v249, v93, v226
	v_exp_f32_e32 v93, v249
	s_waitcnt lgkmcnt(4)
	v_mfma_f32_32x32x16_bf16 v[16:31], v[240:243], v[12:15], v[16:31]
	ds_read_b64 v[240:241], v224 offset:8800
	ds_read_b64 v[242:243], v224 offset:8816
	v_sub_f32_e32 v248, v94, v226
	v_exp_f32_e32 v94, v248
	v_sub_f32_e32 v249, v95, v226
	v_exp_f32_e32 v95, v249
	s_nop 0
	v_cvt_pk_bf16_f32 v8, v88, v89
	v_cvt_pk_bf16_f32 v9, v90, v91
	v_cvt_pk_bf16_f32 v10, v92, v93
	v_cvt_pk_bf16_f32 v11, v94, v95
	s_nop 1
	s_waitcnt lgkmcnt(4)
	v_mfma_f32_32x32x16_bf16 v[64:79], v[232:235], v[8:11], v[64:79]
	ds_read_b64 v[232:233], v224 offset:13152
	ds_read_b64 v[234:235], v224 offset:13168
	v_add_f32_e32 v3, v80, v96
	v_add_f32_e32 v248, v81, v97
	v_add_f32_e32 v3, v248, v3
	v_add_f32_e32 v249, v82, v98
	v_add_f32_e32 v3, v249, v3
	v_add_f32_e32 v248, v83, v99
	v_add_f32_e32 v3, v248, v3
	v_add_f32_e32 v249, v84, v100
	s_waitcnt lgkmcnt(4)
	v_mfma_f32_32x32x16_bf16 v[48:63], v[236:239], v[8:11], v[48:63]
	v_add_f32_e32 v3, v249, v3
	v_add_f32_e32 v248, v85, v101
	v_add_f32_e32 v3, v248, v3
	v_add_f32_e32 v249, v86, v102
	v_add_f32_e32 v3, v249, v3
	v_add_f32_e32 v248, v87, v103
	v_add_f32_e32 v3, v248, v3
	v_add_f32_e32 v249, v88, v104
	s_waitcnt lgkmcnt(2)
	v_mfma_f32_32x32x16_bf16 v[32:47], v[240:243], v[8:11], v[32:47]
	v_add_f32_e32 v3, v249, v3
	v_add_f32_e32 v248, v89, v105
	v_add_f32_e32 v3, v248, v3
	v_add_f32_e32 v249, v90, v106
	v_add_f32_e32 v3, v249, v3
	v_add_f32_e32 v248, v91, v107
	v_add_f32_e32 v3, v248, v3
	v_add_f32_e32 v249, v92, v108
	s_waitcnt lgkmcnt(0)
	v_mfma_f32_32x32x16_bf16 v[16:31], v[232:235], v[8:11], v[16:31]
	v_add_f32_e32 v3, v249, v3
	v_add_f32_e32 v248, v93, v109
	v_add_f32_e32 v3, v248, v3
	v_add_f32_e32 v249, v94, v110
	v_add_f32_e32 v3, v249, v3
	v_add_f32_e32 v248, v95, v111
	v_add_f32_e32 v3, v248, v3
	v_fmac_f32_e32 v3, v221, v0
	v_mov_b32_e32 v221, v3
	s_branch .LBB0_1557
